# mlstmA: gates pre-pass + cross-item software pipelining of conv row loads and K/V tile loads
# speedup vs baseline: 1.0130x; 1.0039x over previous
; DI void conv_unit(const u16* __restrict__ PM, const float* __restrict__ conv_w, const float* __restrict__ conv_b, int b, int sl0, int ch, float scale, float* a8) {
;   { const float4 b0 = *(const float4*)(conv_b + ch), b1 = *(const float4*)(conv_b + ch + 4); a8[0] = b0.x; a8[1] = b0.y; a8[2] = b0.z; a8[3] = b0.w; a8[4] = b1.x; a8[5] = b1.y; a8[6] = b1.z; a8[7] = b1.w; }
; #pragma unroll
;   for (int j = 0; j < 4; ++j) {
;     const int sl = sl0 - 3 + j;
;     if (sl >= 0) {
;       const uint4 raw = *(const uint4*)(PM + ((size_t)b * SEQ + sl) * 1024 + ch);
;       float x8[8]; unpack8(raw, x8);
;       const float4 w0 = *(const float4*)(conv_w + j * 1024 + ch), w1 = *(const float4*)(conv_w + j * 1024 + ch + 4);
;       a8[0] += w0.x * x8[0]; a8[1] += w0.y * x8[1]; a8[2] += w0.z * x8[2]; a8[3] += w0.w * x8[3];
;       a8[4] += w1.x * x8[4]; a8[5] += w1.y * x8[5]; a8[6] += w1.z * x8[6]; a8[7] += w1.w * x8[7];
;     }
;   }
; DI void mlstmA_item(const Params& p, char* lds, int item) {
;     ...
;   for (int i = 0; i < 2; ++i) {
;     const int q = tid + 512 * i, e = q >> 3, s8 = (q & 7) * 8;
;     *(uint4*)(VTs + e * 72 + s8) = *(const uint4*)(VTm + ((size_t)(bh * 128 + e)) * SEQ + c * 64 + s8);
;   }
.Lmg_next:
	s_add_i32 s80, s80, 1
	s_cmp_lt_u32 s80, 2
	s_cbranch_scc1 .Lmg_round
	s_mov_b32 s10, s94
	s_mov_b32 s96, 0
	v_add_u32_e32 v240, 0x200, v222
	s_and_b32 s73, s10, 0xffffff80
	v_lshlrev_b32_e32 v241, 4, v222
	v_ashrrev_i32_e32 v242, 3, v222
	v_ashrrev_i32_e32 v244, 3, v240
	v_and_b32_e32 v246, 0x70, v241
	v_mov_b32_e32 v247, 0
	v_add_u32_e32 v242, s73, v242
	v_add_u32_e32 v244, s73, v244
	s_and_b32 s78, s10, 0x7f
	s_lshl_b32 s78, s78, 7
	v_mov_b32_e32 v248, s78
	v_mov_b32_e32 v249, 0
	v_lshl_add_u64 v[248:249], s[6:7], 0, v[248:249]
	v_lshl_add_u64 v[248:249], v[248:249], 0, v[246:247]
	v_ashrrev_i32_e32 v243, 31, v242
	v_ashrrev_i32_e32 v245, 31, v244
	v_lshlrev_b64 v[242:243], 14, v[242:243]
	v_lshlrev_b64 v[244:245], 14, v[244:245]
	v_lshl_add_u64 v[242:243], v[248:249], 0, v[242:243]
	v_lshl_add_u64 v[244:245], v[248:249], 0, v[244:245]
	global_load_dwordx4 v[232:235], v[242:243], off
	global_load_dwordx4 v[236:239], v[244:245], off
	v_and_b32_e32 v70, 15, v222
	s_bfe_u32 s72, s10, 0x20007
	v_lshlrev_b32_e32 v70, 3, v70
	s_lshl_b32 s72, s72, 7
	v_add_u32_e32 v70, s72, v70
	s_ashr_i32 s74, s10, 9
	s_ashr_i32 s75, s74, 31
	s_lshl_b64 s[74:75], s[74:75], 24
	s_add_u32 s74, s74, s4
	s_addc_u32 s75, s75, s5
	v_lshlrev_b32_e32 v76, 1, v70
	v_mov_b32_e32 v77, 0
	v_lshl_add_u64 v[78:79], s[74:75], 0, v[76:77]
	s_and_b32 s76, s10, 0x7f
	s_lshl_b32 s76, s76, 6
	v_lshrrev_b32_e32 v75, 4, v222
	s_movk_i32 s77, 0x800
	v_add_u32_e32 v184, s76, v75
	v_add_u32_e32 v185, -1, v184
	v_mov_b32_e32 v114, 0
	v_mov_b32_e32 v115, 0
	v_mov_b32_e32 v116, 0
	v_mov_b32_e32 v117, 0
	v_mov_b32_e32 v118, 0
	v_mov_b32_e32 v119, 0
	v_mov_b32_e32 v120, 0
	v_mov_b32_e32 v121, 0
	v_mov_b32_e32 v122, 0
	v_mov_b32_e32 v123, 0
	v_mov_b32_e32 v124, 0
	v_mov_b32_e32 v125, 0
	v_mad_i64_i32 v[186:187], s[88:89], v185, s77, v[78:79]
	v_cmp_lt_i32_e64 s[84:85], 2, v184
	s_and_saveexec_b64 s[86:87], s[84:85]
	global_load_dwordx4 v[114:117], v[186:187], off offset:-3072
	s_or_b64 exec, exec, s[86:87]
	v_cmp_lt_i32_e64 s[84:85], 1, v184
	s_and_saveexec_b64 s[86:87], s[84:85]
	global_load_dwordx4 v[118:121], v[186:187], off offset:-1024
	s_or_b64 exec, exec, s[86:87]
	v_cmp_lt_i32_e64 s[84:85], 0, v184
	s_and_saveexec_b64 s[86:87], s[84:85]
	global_load_dwordx4 v[122:125], v[186:187], off offset:1024
	s_or_b64 exec, exec, s[86:87]
	global_load_dwordx4 v[126:129], v[186:187], off offset:3072
	v_add_u32_e32 v184, 32, v184
	v_add_u32_e32 v185, -1, v184
	v_mov_b32_e32 v130, 0
	v_mov_b32_e32 v131, 0
	v_mov_b32_e32 v132, 0
	v_mov_b32_e32 v133, 0
	v_mov_b32_e32 v134, 0
	v_mov_b32_e32 v135, 0
	v_mov_b32_e32 v136, 0
	v_mov_b32_e32 v137, 0
	v_mov_b32_e32 v172, 0
	v_mov_b32_e32 v173, 0
	v_mov_b32_e32 v174, 0
	v_mov_b32_e32 v175, 0
	v_mad_i64_i32 v[186:187], s[88:89], v185, s77, v[78:79]
	v_cmp_lt_i32_e64 s[84:85], 2, v184
	s_and_saveexec_b64 s[86:87], s[84:85]
	global_load_dwordx4 v[130:133], v[186:187], off offset:-3072
	s_or_b64 exec, exec, s[86:87]
	v_cmp_lt_i32_e64 s[84:85], 1, v184
	s_and_saveexec_b64 s[86:87], s[84:85]
	global_load_dwordx4 v[134:137], v[186:187], off offset:-1024
	s_or_b64 exec, exec, s[86:87]
	v_cmp_lt_i32_e64 s[84:85], 0, v184
	s_and_saveexec_b64 s[86:87], s[84:85]
	global_load_dwordx4 v[172:175], v[186:187], off offset:1024
	s_or_b64 exec, exec, s[86:87]
	global_load_dwordx4 v[176:179], v[186:187], off offset:3072
	s_waitcnt vmcnt(0)
	s_branch .LBB0_324

; DI u16 f2bf(float x) { return (u16)(pack2(x, 0.f) & 0xffffu); }
; DI void conv_unit(const u16* __restrict__ PM, const float* __restrict__ conv_w, const float* __restrict__ conv_b, int b, int sl0, int ch, float scale, float* a8) {
;   { const float4 b0 = *(const float4*)(conv_b + ch), b1 = *(const float4*)(conv_b + ch + 4); a8[0] = b0.x; a8[1] = b0.y; a8[2] = b0.z; a8[3] = b0.w; a8[4] = b1.x; a8[5] = b1.y; a8[6] = b1.z; a8[7] = b1.w; }
; #pragma unroll
;   for (int j = 0; j < 4; ++j) {
;     const int sl = sl0 - 3 + j;
;     if (sl >= 0) {
;       const uint4 raw = *(const uint4*)(PM + ((size_t)b * SEQ + sl) * 1024 + ch);
;       float x8[8]; unpack8(raw, x8);
;       const float4 w0 = *(const float4*)(conv_w + j * 1024 + ch), w1 = *(const float4*)(conv_w + j * 1024 + ch + 4);
;       a8[0] += w0.x * x8[0]; a8[1] += w0.y * x8[1]; a8[2] += w0.z * x8[2]; a8[3] += w0.w * x8[3];
;       a8[4] += w1.x * x8[4]; a8[5] += w1.y * x8[5]; a8[6] += w1.z * x8[6]; a8[7] += w1.w * x8[7];
;     }
;   }
; #pragma unroll
;   for (int e = 0; e < 8; ++e) { const float v = a8[e]; a8[e] = scale * v * __builtin_amdgcn_rcpf(1.f + __expf(-v)); }
; DI void mlstmA_item(const Params& p, char* lds, int item) {
;     ...
;   for (int i = 0; i < 2; ++i) {
;     const int q = tid + 512 * i, e = q >> 3, s8 = (q & 7) * 8;
;     *(uint4*)(VTs + e * 72 + s8) = *(const uint4*)(VTm + ((size_t)(bh * 128 + e)) * SEQ + c * 64 + s8);
;   }
;   __syncthreads();
; #pragma unroll 1
;   for (int i = 0; i < 2; ++i) {
;     const int cgk = tid & 15, t = (tid >> 4) + 32 * i;
;     float a8[8];
;     conv_unit(PM, p.in[5], p.in[6], b, c * 64 + t, 512 + hd * 128 + cgk * 8, 0.08838834764831845f, a8);
;     const float w = win[t];
; #pragma unroll
;     for (int e = 0; e < 8; ++e) KTs[(cgk * 8 + e) * 72 + t] = f2bf(a8[e] * w);
.LBB0_324:
	v_and_b32_e32 v70, 15, v222
	s_bfe_u32 s72, s10, 0x20007
	v_lshlrev_b32_e32 v70, 3, v70
	s_lshl_b32 s72, s72, 7
	v_add_u32_e32 v70, s72, v70
	v_lshlrev_b32_e32 v71, 2, v70
	v_add_u32_e32 v72, 0x1000, v71
	v_add_u32_e32 v73, 0x2000, v71
	v_add_u32_e32 v74, 0x3000, v71
	global_load_dwordx4 v[140:143], v71, s[62:63] offset:2048
	global_load_dwordx4 v[144:147], v71, s[62:63] offset:2064
	global_load_dwordx4 v[148:151], v72, s[62:63] offset:2048
	global_load_dwordx4 v[152:155], v72, s[62:63] offset:2064
	global_load_dwordx4 v[156:159], v73, s[62:63] offset:2048
	global_load_dwordx4 v[160:163], v73, s[62:63] offset:2064
	global_load_dwordx4 v[164:167], v74, s[62:63] offset:2048
	global_load_dwordx4 v[168:171], v74, s[62:63] offset:2064
	global_load_dwordx4 v[224:227], v71, s[64:65] offset:2048
	global_load_dwordx4 v[228:231], v71, s[64:65] offset:2064
	v_mov_b32_e32 v18, v222
	s_and_b32 s18, s10, 0x7f
	s_ashr_i32 s12, s10, 9
	s_nop 0
	v_cmp_lt_u32_e32 vcc, 63, v18
	s_and_saveexec_b64 s[0:1], vcc
	s_xor_b64 s[0:1], exec, s[0:1]
	s_lshl_b32 s8, s18, 6
	s_ashr_i32 s13, s12, 31
	s_or_saveexec_b64 s[14:15], s[0:1]
	s_bfe_u32 s27, s10, 0x20007
	v_and_b32_e32 v19, 63, v18
	s_ashr_i32 s11, s10, 31
	v_mov_b64_e32 v[10:11], s[12:13]
	v_mov_b64_e32 v[0:1], s[8:9]
	v_mov_b32_e32 v50, s8
.LBB0_330:
	s_or_b64 exec, exec, s[14:15]
	v_add_u32_e32 v4, 0x200, v18
	s_and_b32 s0, s10, 0xffffff80
	v_lshlrev_b32_e32 v2, 4, v18
	v_ashrrev_i32_e32 v9, 3, v18
	v_ashrrev_i32_e32 v14, 3, v4
	v_and_b32_e32 v16, 0x70, v2
	v_add_u32_e32 v2, s0, v9
	v_add_u32_e32 v4, s0, v14
	v_lshl_add_u64 v[0:1], v[0:1], 1, s[6:7]
	v_ashrrev_i32_e32 v3, 31, v2
	v_ashrrev_i32_e32 v5, 31, v4
	v_lshl_add_u64 v[0:1], v[0:1], 0, v[16:17]
	v_lshlrev_b64 v[2:3], 14, v[2:3]
	v_lshlrev_b64 v[4:5], 14, v[4:5]
	v_lshl_add_u64 v[2:3], v[0:1], 0, v[2:3]
	v_lshl_add_u64 v[4:5], v[0:1], 0, v[4:5]
	v_lshlrev_b32_e32 v8, 3, v18
	v_and_b32_e32 v22, 0x78, v8
	v_add_u32_e32 v8, 0, v16
	v_lshl_or_b32 v15, s27, 7, v22
	v_mad_u64_u32 v[12:13], s[0:1], v9, s26, v[8:9]
	v_lshlrev_b32_e32 v16, 2, v15
	v_mad_u64_u32 v[8:9], s[0:1], v14, s26, v[8:9]
	v_lshlrev_b64 v[10:11], 24, v[10:11]
	v_lshl_add_u64 v[10:11], s[4:5], 0, v[10:11]
	v_mov_b32_e32 v13, v17
	s_mov_b64 s[0:1], 0x1800
	v_ashrrev_i32_e32 v51, 4, v18
	v_mad_u32_u24 v52, v22, s26, 0
	s_mov_b32 s8, 0
	s_waitcnt vmcnt(20)
	ds_write_b128 v12, v[232:235] offset:18432
	ds_write_b128 v8, v[236:239] offset:18432
	s_waitcnt lgkmcnt(0)
	s_barrier
	s_add_i32 s97, s10, s70
	v_add_u32_e32 v240, 0x200, v222
	s_and_b32 s73, s97, 0xffffff80
	v_lshlrev_b32_e32 v241, 4, v222
	v_ashrrev_i32_e32 v242, 3, v222
	v_ashrrev_i32_e32 v244, 3, v240
	v_and_b32_e32 v246, 0x70, v241
	v_mov_b32_e32 v247, 0
	v_add_u32_e32 v242, s73, v242
	v_add_u32_e32 v244, s73, v244
	s_and_b32 s78, s97, 0x7f
	s_lshl_b32 s78, s78, 7
	v_mov_b32_e32 v248, s78
	v_mov_b32_e32 v249, 0
	v_lshl_add_u64 v[248:249], s[6:7], 0, v[248:249]
	v_lshl_add_u64 v[248:249], v[248:249], 0, v[246:247]
	v_ashrrev_i32_e32 v243, 31, v242
	v_ashrrev_i32_e32 v245, 31, v244
	v_lshlrev_b64 v[242:243], 14, v[242:243]
	v_lshlrev_b64 v[244:245], 14, v[244:245]
	v_lshl_add_u64 v[242:243], v[248:249], 0, v[242:243]
	v_lshl_add_u64 v[244:245], v[248:249], 0, v[244:245]
	global_load_dwordx4 v[232:235], v[242:243], off
	global_load_dwordx4 v[236:239], v[244:245], off
	s_waitcnt vmcnt(2)
	v_mov_b32_e32 v197, v51
	v_lshl_add_u32 v196, v197, 2, s96
	ds_read_b32 v196, v196 offset:40960
	v_lshl_add_u32 v198, v197, 1, v52
	v_lshlrev_b32_e32 v188, 16, v114
	v_and_b32_e32 v189, 0xffff0000, v114
	v_lshlrev_b32_e32 v190, 16, v115
	v_and_b32_e32 v191, 0xffff0000, v115
	v_lshlrev_b32_e32 v192, 16, v116
	v_and_b32_e32 v193, 0xffff0000, v116
	v_lshlrev_b32_e32 v194, 16, v117
	v_and_b32_e32 v195, 0xffff0000, v117
	v_pk_fma_f32 v[204:205], v[140:141], v[188:189], v[224:225]
	v_pk_fma_f32 v[206:207], v[142:143], v[190:191], v[226:227]
	v_pk_fma_f32 v[208:209], v[144:145], v[192:193], v[228:229]
	v_pk_fma_f32 v[210:211], v[146:147], v[194:195], v[230:231]
	v_lshlrev_b32_e32 v188, 16, v118
	v_and_b32_e32 v189, 0xffff0000, v118
	v_lshlrev_b32_e32 v190, 16, v119
	v_and_b32_e32 v191, 0xffff0000, v119
	v_lshlrev_b32_e32 v192, 16, v120
	v_and_b32_e32 v193, 0xffff0000, v120
	v_lshlrev_b32_e32 v194, 16, v121
	v_and_b32_e32 v195, 0xffff0000, v121
	v_pk_fma_f32 v[204:205], v[148:149], v[188:189], v[204:205]
	v_pk_fma_f32 v[206:207], v[150:151], v[190:191], v[206:207]
	v_pk_fma_f32 v[208:209], v[152:153], v[192:193], v[208:209]
	v_pk_fma_f32 v[210:211], v[154:155], v[194:195], v[210:211]
	v_lshlrev_b32_e32 v188, 16, v122
	v_and_b32_e32 v189, 0xffff0000, v122
	v_lshlrev_b32_e32 v190, 16, v123
	v_and_b32_e32 v191, 0xffff0000, v123
	v_lshlrev_b32_e32 v192, 16, v124
	v_and_b32_e32 v193, 0xffff0000, v124
	v_lshlrev_b32_e32 v194, 16, v125
	v_and_b32_e32 v195, 0xffff0000, v125
	v_pk_fma_f32 v[204:205], v[156:157], v[188:189], v[204:205]
	v_pk_fma_f32 v[206:207], v[158:159], v[190:191], v[206:207]
	v_pk_fma_f32 v[208:209], v[160:161], v[192:193], v[208:209]
	v_pk_fma_f32 v[210:211], v[162:163], v[194:195], v[210:211]
	v_lshlrev_b32_e32 v188, 16, v126
	v_and_b32_e32 v189, 0xffff0000, v126
	v_lshlrev_b32_e32 v190, 16, v127
	v_and_b32_e32 v191, 0xffff0000, v127
	v_lshlrev_b32_e32 v192, 16, v128
	v_and_b32_e32 v193, 0xffff0000, v128
	v_lshlrev_b32_e32 v194, 16, v129
	v_and_b32_e32 v195, 0xffff0000, v129
	v_pk_fma_f32 v[204:205], v[164:165], v[188:189], v[204:205]
	v_pk_fma_f32 v[206:207], v[166:167], v[190:191], v[206:207]
	v_pk_fma_f32 v[208:209], v[168:169], v[192:193], v[208:209]
	v_pk_fma_f32 v[210:211], v[170:171], v[194:195], v[210:211]
; DI u16 f2bf(float x) { return (u16)(pack2(x, 0.f) & 0xffffu); }
; DI void conv_unit(const u16* __restrict__ PM, const float* __restrict__ conv_w, const float* __restrict__ conv_b, int b, int sl0, int ch, float scale, float* a8) {
;     ...
;   for (int j = 0; j < 4; ++j) {
;     const int sl = sl0 - 3 + j;
;     if (sl >= 0) {
;       const uint4 raw = *(const uint4*)(PM + ((size_t)b * SEQ + sl) * 1024 + ch);
;       float x8[8]; unpack8(raw, x8);
;       const float4 w0 = *(const float4*)(conv_w + j * 1024 + ch), w1 = *(const float4*)(conv_w + j * 1024 + ch + 4);
;       a8[0] += w0.x * x8[0]; a8[1] += w0.y * x8[1]; a8[2] += w0.z * x8[2]; a8[3] += w0.w * x8[3];
;       a8[4] += w1.x * x8[4]; a8[5] += w1.y * x8[5]; a8[6] += w1.z * x8[6]; a8[7] += w1.w * x8[7];
;     }
;   }
; #pragma unroll
;   for (int e = 0; e < 8; ++e) { const float v = a8[e]; a8[e] = scale * v * __builtin_amdgcn_rcpf(1.f + __expf(-v)); }
; DI void mlstmA_item(const Params& p, char* lds, int item) {
;     ...
;   for (int i = 0; i < 2; ++i) {
;     const int cgk = tid & 15, t = (tid >> 4) + 32 * i;
;     float a8[8];
;     conv_unit(PM, p.in[5], p.in[6], b, c * 64 + t, 512 + hd * 128 + cgk * 8, 0.08838834764831845f, a8);
;     const float w = win[t];
; #pragma unroll
;     for (int e = 0; e < 8; ++e) KTs[(cgk * 8 + e) * 72 + t] = f2bf(a8[e] * w);
	v_mul_f32_e32 v212, 0xbfb8aa3b, v204
	v_mul_f32_e32 v213, 0xbfb8aa3b, v205
	v_mul_f32_e32 v214, 0xbfb8aa3b, v206
	v_mul_f32_e32 v215, 0xbfb8aa3b, v207
	v_mul_f32_e32 v216, 0xbfb8aa3b, v208
	v_mul_f32_e32 v217, 0xbfb8aa3b, v209
	v_mul_f32_e32 v218, 0xbfb8aa3b, v210
	v_mul_f32_e32 v219, 0xbfb8aa3b, v211
	v_mul_f32_e32 v188, 0x3db504f3, v204
	v_mul_f32_e32 v189, 0x3db504f3, v205
	v_mul_f32_e32 v190, 0x3db504f3, v206
	v_mul_f32_e32 v191, 0x3db504f3, v207
	v_mul_f32_e32 v192, 0x3db504f3, v208
	v_mul_f32_e32 v193, 0x3db504f3, v209
	v_mul_f32_e32 v194, 0x3db504f3, v210
	v_mul_f32_e32 v195, 0x3db504f3, v211
	v_exp_f32_e32 v212, v212
	v_exp_f32_e32 v213, v213
	v_exp_f32_e32 v214, v214
	v_exp_f32_e32 v215, v215
	v_exp_f32_e32 v216, v216
	v_exp_f32_e32 v217, v217
	v_exp_f32_e32 v218, v218
	v_exp_f32_e32 v219, v219
	v_add_f32_e32 v212, 1.0, v212
	v_add_f32_e32 v213, 1.0, v213
	v_add_f32_e32 v214, 1.0, v214
	v_add_f32_e32 v215, 1.0, v215
	v_add_f32_e32 v216, 1.0, v216
	v_add_f32_e32 v217, 1.0, v217
	v_add_f32_e32 v218, 1.0, v218
	v_add_f32_e32 v219, 1.0, v219
	v_rcp_f32_e32 v212, v212
	v_rcp_f32_e32 v213, v213
	v_rcp_f32_e32 v214, v214
	v_rcp_f32_e32 v215, v215
	v_rcp_f32_e32 v216, v216
	v_rcp_f32_e32 v217, v217
	v_rcp_f32_e32 v218, v218
	v_rcp_f32_e32 v219, v219
	v_mul_f32_e32 v188, v188, v212
	v_mul_f32_e32 v189, v189, v213
	v_mul_f32_e32 v190, v190, v214
	v_mul_f32_e32 v191, v191, v215
	v_mul_f32_e32 v192, v192, v216
	v_mul_f32_e32 v193, v193, v217
	v_mul_f32_e32 v194, v194, v218
	v_mul_f32_e32 v195, v195, v219
	s_waitcnt lgkmcnt(0)
	v_mul_f32_e32 v188, v196, v188
	v_mul_f32_e32 v189, v196, v189
	v_mul_f32_e32 v190, v196, v190
	v_mul_f32_e32 v191, v196, v191
	v_mul_f32_e32 v192, v196, v192
	v_mul_f32_e32 v193, v196, v193
	v_mul_f32_e32 v194, v196, v194
	v_mul_f32_e32 v195, v196, v195
	v_cvt_pk_bf16_f32 v188, v188, s77
	v_cvt_pk_bf16_f32 v189, v189, s77
	v_cvt_pk_bf16_f32 v190, v190, s77
	v_cvt_pk_bf16_f32 v191, v191, s77
	v_cvt_pk_bf16_f32 v192, v192, s77
	v_cvt_pk_bf16_f32 v193, v193, s77
	v_cvt_pk_bf16_f32 v194, v194, s77
	v_cvt_pk_bf16_f32 v195, v195, s77
	ds_write_b16 v198, v188
	ds_write_b16 v198, v189 offset:144
	ds_write_b16 v198, v190 offset:288
	ds_write_b16 v198, v191 offset:432
	ds_write_b16 v198, v192 offset:576
	ds_write_b16 v198, v193 offset:720
	ds_write_b16 v198, v194 offset:864
	ds_write_b16 v198, v195 offset:1008
	v_add_u32_e32 v197, 32, v51
	v_lshl_add_u32 v196, v197, 2, s96
	ds_read_b32 v196, v196 offset:40960
	v_lshl_add_u32 v198, v197, 1, v52
	v_lshlrev_b32_e32 v188, 16, v130
	v_and_b32_e32 v189, 0xffff0000, v130
	v_lshlrev_b32_e32 v190, 16, v131
	v_and_b32_e32 v191, 0xffff0000, v131
	v_lshlrev_b32_e32 v192, 16, v132
	v_and_b32_e32 v193, 0xffff0000, v132
	v_lshlrev_b32_e32 v194, 16, v133
	v_and_b32_e32 v195, 0xffff0000, v133
	v_pk_fma_f32 v[204:205], v[140:141], v[188:189], v[224:225]
	v_pk_fma_f32 v[206:207], v[142:143], v[190:191], v[226:227]
	v_pk_fma_f32 v[208:209], v[144:145], v[192:193], v[228:229]
	v_pk_fma_f32 v[210:211], v[146:147], v[194:195], v[230:231]
	v_lshlrev_b32_e32 v188, 16, v134
	v_and_b32_e32 v189, 0xffff0000, v134
	v_lshlrev_b32_e32 v190, 16, v135
	v_and_b32_e32 v191, 0xffff0000, v135
	v_lshlrev_b32_e32 v192, 16, v136
	v_and_b32_e32 v193, 0xffff0000, v136
	v_lshlrev_b32_e32 v194, 16, v137
	v_and_b32_e32 v195, 0xffff0000, v137
	v_pk_fma_f32 v[204:205], v[148:149], v[188:189], v[204:205]
	v_pk_fma_f32 v[206:207], v[150:151], v[190:191], v[206:207]
	v_pk_fma_f32 v[208:209], v[152:153], v[192:193], v[208:209]
	v_pk_fma_f32 v[210:211], v[154:155], v[194:195], v[210:211]
	v_lshlrev_b32_e32 v188, 16, v172
	v_and_b32_e32 v189, 0xffff0000, v172
	v_lshlrev_b32_e32 v190, 16, v173
	v_and_b32_e32 v191, 0xffff0000, v173
	v_lshlrev_b32_e32 v192, 16, v174
	v_and_b32_e32 v193, 0xffff0000, v174
	v_lshlrev_b32_e32 v194, 16, v175
	v_and_b32_e32 v195, 0xffff0000, v175
	v_pk_fma_f32 v[204:205], v[156:157], v[188:189], v[204:205]
	v_pk_fma_f32 v[206:207], v[158:159], v[190:191], v[206:207]
	v_pk_fma_f32 v[208:209], v[160:161], v[192:193], v[208:209]
	v_pk_fma_f32 v[210:211], v[162:163], v[194:195], v[210:211]
	v_lshlrev_b32_e32 v188, 16, v176
	v_and_b32_e32 v189, 0xffff0000, v176
	v_lshlrev_b32_e32 v190, 16, v177
	v_and_b32_e32 v191, 0xffff0000, v177
	v_lshlrev_b32_e32 v192, 16, v178
	v_and_b32_e32 v193, 0xffff0000, v178
	v_lshlrev_b32_e32 v194, 16, v179
	v_and_b32_e32 v195, 0xffff0000, v179
	v_pk_fma_f32 v[204:205], v[164:165], v[188:189], v[204:205]
	v_pk_fma_f32 v[206:207], v[166:167], v[190:191], v[206:207]
	v_pk_fma_f32 v[208:209], v[168:169], v[192:193], v[208:209]
	v_pk_fma_f32 v[210:211], v[170:171], v[194:195], v[210:211]
	v_mul_f32_e32 v212, 0xbfb8aa3b, v204
	v_mul_f32_e32 v213, 0xbfb8aa3b, v205
	v_mul_f32_e32 v214, 0xbfb8aa3b, v206
	v_mul_f32_e32 v215, 0xbfb8aa3b, v207
	v_mul_f32_e32 v216, 0xbfb8aa3b, v208
	v_mul_f32_e32 v217, 0xbfb8aa3b, v209
	v_mul_f32_e32 v218, 0xbfb8aa3b, v210
	v_mul_f32_e32 v219, 0xbfb8aa3b, v211
	v_mul_f32_e32 v188, 0x3db504f3, v204
	v_mul_f32_e32 v189, 0x3db504f3, v205
	v_mul_f32_e32 v190, 0x3db504f3, v206
	v_mul_f32_e32 v191, 0x3db504f3, v207
	v_mul_f32_e32 v192, 0x3db504f3, v208
	v_mul_f32_e32 v193, 0x3db504f3, v209
	v_mul_f32_e32 v194, 0x3db504f3, v210
	v_mul_f32_e32 v195, 0x3db504f3, v211
	v_exp_f32_e32 v212, v212
	v_exp_f32_e32 v213, v213
	v_exp_f32_e32 v214, v214
	v_exp_f32_e32 v215, v215
	v_exp_f32_e32 v216, v216
	v_exp_f32_e32 v217, v217
	v_exp_f32_e32 v218, v218
	v_exp_f32_e32 v219, v219
	v_add_f32_e32 v212, 1.0, v212
	v_add_f32_e32 v213, 1.0, v213
	v_add_f32_e32 v214, 1.0, v214
	v_add_f32_e32 v215, 1.0, v215
	v_add_f32_e32 v216, 1.0, v216
	v_add_f32_e32 v217, 1.0, v217
	v_add_f32_e32 v218, 1.0, v218
	v_add_f32_e32 v219, 1.0, v219
	v_rcp_f32_e32 v212, v212
	v_rcp_f32_e32 v213, v213
	v_rcp_f32_e32 v214, v214
	v_rcp_f32_e32 v215, v215
	v_rcp_f32_e32 v216, v216
	v_rcp_f32_e32 v217, v217
	v_rcp_f32_e32 v218, v218
	v_rcp_f32_e32 v219, v219
	v_mul_f32_e32 v188, v188, v212
	v_mul_f32_e32 v189, v189, v213
	v_mul_f32_e32 v190, v190, v214
	v_mul_f32_e32 v191, v191, v215
	v_mul_f32_e32 v192, v192, v216
	v_mul_f32_e32 v193, v193, v217
	v_mul_f32_e32 v194, v194, v218
	v_mul_f32_e32 v195, v195, v219
	s_waitcnt lgkmcnt(0)
; DI u16 f2bf(float x) { return (u16)(pack2(x, 0.f) & 0xffffu); }
; DI void conv_unit(const u16* __restrict__ PM, const float* __restrict__ conv_w, const float* __restrict__ conv_b, int b, int sl0, int ch, float scale, float* a8) {
;   { const float4 b0 = *(const float4*)(conv_b + ch), b1 = *(const float4*)(conv_b + ch + 4); a8[0] = b0.x; a8[1] = b0.y; a8[2] = b0.z; a8[3] = b0.w; a8[4] = b1.x; a8[5] = b1.y; a8[6] = b1.z; a8[7] = b1.w; }
; #pragma unroll
;   for (int j = 0; j < 4; ++j) {
;     const int sl = sl0 - 3 + j;
;     if (sl >= 0) {
;       const uint4 raw = *(const uint4*)(PM + ((size_t)b * SEQ + sl) * 1024 + ch);
;       float x8[8]; unpack8(raw, x8);
;       const float4 w0 = *(const float4*)(conv_w + j * 1024 + ch), w1 = *(const float4*)(conv_w + j * 1024 + ch + 4);
;       a8[0] += w0.x * x8[0]; a8[1] += w0.y * x8[1]; a8[2] += w0.z * x8[2]; a8[3] += w0.w * x8[3];
;       a8[4] += w1.x * x8[4]; a8[5] += w1.y * x8[5]; a8[6] += w1.z * x8[6]; a8[7] += w1.w * x8[7];
;     }
;   }
; DI void mlstmA_item(const Params& p, char* lds, int item) {
;     ...
;     const float w = win[t];
; #pragma unroll
;     for (int e = 0; e < 8; ++e) KTs[(cgk * 8 + e) * 72 + t] = f2bf(a8[e] * w);
	v_mul_f32_e32 v188, v196, v188
	v_mul_f32_e32 v189, v196, v189
	v_mul_f32_e32 v190, v196, v190
	v_mul_f32_e32 v191, v196, v191
	v_mul_f32_e32 v192, v196, v192
	v_mul_f32_e32 v193, v196, v193
	v_mul_f32_e32 v194, v196, v194
	v_mul_f32_e32 v195, v196, v195
	v_cvt_pk_bf16_f32 v188, v188, s77
	v_cvt_pk_bf16_f32 v189, v189, s77
	v_cvt_pk_bf16_f32 v190, v190, s77
	v_cvt_pk_bf16_f32 v191, v191, s77
	v_cvt_pk_bf16_f32 v192, v192, s77
	v_cvt_pk_bf16_f32 v193, v193, s77
	v_cvt_pk_bf16_f32 v194, v194, s77
	v_cvt_pk_bf16_f32 v195, v195, s77
	ds_write_b16 v198, v188
	ds_write_b16 v198, v189 offset:144
	ds_write_b16 v198, v190 offset:288
	ds_write_b16 v198, v191 offset:432
	ds_write_b16 v198, v192 offset:576
	ds_write_b16 v198, v193 offset:720
	ds_write_b16 v198, v194 offset:864
	ds_write_b16 v198, v195 offset:1008
	s_add_i32 s97, s10, s70
	v_and_b32_e32 v70, 15, v222
	s_bfe_u32 s72, s97, 0x20007
	v_lshlrev_b32_e32 v70, 3, v70
	s_lshl_b32 s72, s72, 7
	v_add_u32_e32 v70, s72, v70
	s_ashr_i32 s74, s97, 9
	s_ashr_i32 s75, s74, 31
	s_lshl_b64 s[74:75], s[74:75], 24
	s_add_u32 s74, s74, s4
	s_addc_u32 s75, s75, s5
	v_lshlrev_b32_e32 v76, 1, v70
	v_mov_b32_e32 v77, 0
	v_lshl_add_u64 v[78:79], s[74:75], 0, v[76:77]
	s_and_b32 s76, s97, 0x7f
	s_lshl_b32 s76, s76, 6
	v_lshrrev_b32_e32 v75, 4, v222
	s_movk_i32 s77, 0x800
	v_add_u32_e32 v184, s76, v75
	v_add_u32_e32 v185, -1, v184
	v_mov_b32_e32 v114, 0
	v_mov_b32_e32 v115, 0
	v_mov_b32_e32 v116, 0
	v_mov_b32_e32 v117, 0
	v_mov_b32_e32 v118, 0
	v_mov_b32_e32 v119, 0
	v_mov_b32_e32 v120, 0
	v_mov_b32_e32 v121, 0
	v_mov_b32_e32 v122, 0
	v_mov_b32_e32 v123, 0
	v_mov_b32_e32 v124, 0
	v_mov_b32_e32 v125, 0
	v_mad_i64_i32 v[186:187], s[88:89], v185, s77, v[78:79]
	v_cmp_lt_i32_e64 s[84:85], 2, v184
	s_and_saveexec_b64 s[86:87], s[84:85]
	global_load_dwordx4 v[114:117], v[186:187], off offset:-3072
	s_or_b64 exec, exec, s[86:87]
	v_cmp_lt_i32_e64 s[84:85], 1, v184
	s_and_saveexec_b64 s[86:87], s[84:85]
	global_load_dwordx4 v[118:121], v[186:187], off offset:-1024
	s_or_b64 exec, exec, s[86:87]
	v_cmp_lt_i32_e64 s[84:85], 0, v184
	s_and_saveexec_b64 s[86:87], s[84:85]
	global_load_dwordx4 v[122:125], v[186:187], off offset:1024
	s_or_b64 exec, exec, s[86:87]
	global_load_dwordx4 v[126:129], v[186:187], off offset:3072
	v_add_u32_e32 v184, 32, v184
	v_add_u32_e32 v185, -1, v184
	v_mov_b32_e32 v130, 0
	v_mov_b32_e32 v131, 0
	v_mov_b32_e32 v132, 0
	v_mov_b32_e32 v133, 0
	v_mov_b32_e32 v134, 0
	v_mov_b32_e32 v135, 0
	v_mov_b32_e32 v136, 0
	v_mov_b32_e32 v137, 0
	v_mov_b32_e32 v172, 0
	v_mov_b32_e32 v173, 0
	v_mov_b32_e32 v174, 0
	v_mov_b32_e32 v175, 0
	v_mad_i64_i32 v[186:187], s[88:89], v185, s77, v[78:79]
	v_cmp_lt_i32_e64 s[84:85], 2, v184
	s_and_saveexec_b64 s[86:87], s[84:85]
	global_load_dwordx4 v[130:133], v[186:187], off offset:-3072
	s_or_b64 exec, exec, s[86:87]
	v_cmp_lt_i32_e64 s[84:85], 1, v184
	s_and_saveexec_b64 s[86:87], s[84:85]
	global_load_dwordx4 v[134:137], v[186:187], off offset:-1024
	s_or_b64 exec, exec, s[86:87]
	v_cmp_lt_i32_e64 s[84:85], 0, v184
	s_and_saveexec_b64 s[86:87], s[84:85]
	global_load_dwordx4 v[172:175], v[186:187], off offset:1024
	s_or_b64 exec, exec, s[86:87]
	global_load_dwordx4 v[176:179], v[186:187], off offset:3072

; DI int otid() { int t = __builtin_amdgcn_workitem_id_x(); asm volatile("" : "+v"(t)); return t; }
; DI int perm23(int i) { return (i & 0x13) | (((i >> 3) & 1) << 2) | (((i >> 2) & 1) << 3); }
; DI void attn_item(const Params& p, char* lds, int item) {
;   char* ws = p.ws;
;   const int tid = otid(), lane = tid & 63, wave = tid >> 6, l31 = lane & 31, hh = lane >> 5;
;   const int b = item >> 8, h = (item >> 5) & 7, c0 = (item & 31) * 4;
;   const int qc = c0 + (wave >> 1), qt = wave & 1;
;   const u16* PA = (const u16*)(ws + OFF_PA); const u16* VTa = (const u16*)(ws + OFF_VTA); u16* MIX = (u16*)(ws + OFF_MIX);
;   u16* Kl = (u16*)lds;
;   u16* Vl = Kl + 2 * 64 * 72;
;   float* biasl = (float*)(Vl + 2 * 64 * 72);
;   const int pi = perm23(l31);
;   const int sr = tid >> 3, sc8 = (tid & 7) * 8;
;   const u16* kg = PA + ((size_t)b * SEQ + sr) * 1024 + 512 + h * 64 + sc8;
;   const u16* vg = VTa + ((size_t)((b * 8 + h) * 64 + sr)) * SEQ + sc8;
;   for (int i = tid; i < 257; i += 512) biasl[i] = p.in[10][h * 257 + i] * 1.4426950408889634f;
; DI void phase_mixA(const Params& p, char* lds) {
;   for (int it = blockIdx.x; it < 4096; it += gridDim.x) mlstmA_item(p, lds, it);
;   if ((gridDim.x & 7) == 0 && gridDim.x <= 256) {
;     const int x = blockIdx.x & 7, slot = blockIdx.x >> 3, nx = gridDim.x >> 3;
;     for (int j = slot; j < 256; j += nx) attn_item(p, lds, x * 256 + j);
;   } else {
;     for (int it = blockIdx.x; it < 2048; it += gridDim.x) attn_item(p, lds, it);
.LBB0_342:
	s_waitcnt vmcnt(0)
	v_readlane_b32 s4, v250, 0
	v_readlane_b32 s5, v250, 1
	s_load_dword s0, s[4:5], 0x10
	s_load_dword s2, s[4:5], 0x0
	s_waitcnt lgkmcnt(0)
	s_lshr_b32 s0, s0, 16
	s_cmp_lg_u32 s0, 0
	s_cselect_b64 s[0:1], -1, 0
	s_cmp_lg_u64 s[0:1], 0
	s_addc_u32 s2, s2, 0
	s_and_b32 s0, s2, 7
	s_cmp_eq_u32 s0, 0
	s_cselect_b64 s[0:1], -1, 0
	s_cmpk_lt_u32 s2, 0x101
	s_cselect_b64 s[4:5], -1, 0
	s_and_b64 s[4:5], s[4:5], s[0:1]
	s_mov_b64 s[0:1], -1
	s_and_b64 vcc, exec, s[4:5]
	s_cbranch_vccnz .LBB0_376
	s_cmpk_gt_i32 s94, 0x7ff
	s_cbranch_scc1 .LBB0_375
	s_add_u32 s4, s68, 0x2a800000
	s_addc_u32 s5, s69, 0
	s_add_u32 s6, s68, 0x1e800000
	s_addc_u32 s7, s69, 0
	s_lshl_b32 s13, s94, 2
	s_lshl_b32 s15, s2, 2
	s_movk_i32 s8, 0x800
	s_mov_b32 s11, 0
	s_add_i32 s34, 0, 0x9000
	s_mov_b32 s12, 0x3fb8aa3b
	v_mov_b32_e32 v1, 0
	s_movk_i32 s35, 0x90
	s_movk_i32 s42, 0xff61
	s_movk_i32 s43, 0xff80
	s_mov_b32 s14, 0x3e38aa3b
	s_movk_i32 s48, 0xff7f
	s_mov_b32 s49, 0xff800000
	s_movk_i32 s50, 0xff7e
	s_movk_i32 s51, 0xff7d
	s_movk_i32 s54, 0xff7c
	s_movk_i32 s55, 0xff7b
	s_movk_i32 s56, 0xff7a
	s_movk_i32 s57, 0xff79
	s_movk_i32 s58, 0xff70
	s_movk_i32 s59, 0xff6f
	s_movk_i32 s60, 0xff6e
	s_movk_i32 s61, 0xff6d
	s_movk_i32 s72, 0xff6c
	s_movk_i32 s73, 0xff6b
	s_movk_i32 s74, 0xff6a
	s_movk_i32 s75, 0xff69
	v_mbcnt_hi_u32_b32 v114, -1, v203
	v_mov_b32_e32 v115, 0x80
	v_mov_b32_e32 v116, 0x7f
	v_mov_b32_e32 v117, 0x7e
	v_mov_b32_e32 v118, 0x7d
	v_mov_b32_e32 v119, 0x7c
	v_mov_b32_e32 v120, 0x7b
	v_mov_b32_e32 v121, 0x7a
	v_mov_b32_e32 v122, 0x79
	v_mov_b32_e32 v123, 0x70
	v_mov_b32_e32 v124, 0x6f
	v_mov_b32_e32 v125, 0x6e
	v_mov_b32_e32 v126, 0x6d
	v_mov_b32_e32 v127, 0x6c
	v_mov_b32_e32 v128, 0x6b
	v_mov_b32_e32 v129, 0x6a
	v_mov_b32_e32 v130, 0x69
	s_mov_b32 s76, s94
	s_branch .LBB0_346
